# attn: bpermute off common path, mov-free row-sum tree, MLA LDS frag prefetch + Q in regs
# speedup vs baseline: 1.0001x; 1.0001x over previous
; #define ATT_BAR() do { asm volatile("s_waitcnt lgkmcnt(0)" ::: "memory"); __builtin_amdgcn_s_barrier(); asm volatile("" ::: "memory"); } while (0)
; template <int DK, int DV>
; __device__ __forceinline__ void attn_unit(LAS unsigned char* lds, const bf16* Qp, int ldq, const bf16* Kp, int ldk, const bf16* VTp, bf16* Op, int ldo, int qb) {
;     ...
;     float mrun = 0.f, lrun = 0.f;
;     f32x16 o[NDB];
; #pragma unroll
;     for (int db = 0; db < NDB; ++db)
; #pragma unroll
;         for (int r = 0; r < 16; ++r) o[db][r] = 0.f;
;     f32x16 s0, s1;
;     const f32x16 zacc = {0.f, 0.f, 0.f, 0.f, 0.f, 0.f, 0.f, 0.f, 0.f, 0.f, 0.f, 0.f, 0.f, 0.f, 0.f, 0.f};
;     f32x16 negm = zacc;
;     constexpr float ATT_THR = 8.f;
;     ATT_QK(0, zacc);
;     if (grpB) ATT_BAR();
;     int bcur = 0, bnext = BUF, bfree = 2 * BUF;
.LBB0_1036:
	ds_read_b128 v[196:199], v141
	ds_read_b128 v[200:203], v141 offset:1024
	ds_read_b128 v[204:207], v141 offset:2048
	ds_read_b128 v[208:211], v141 offset:3072
	ds_read_b128 v[212:215], v141 offset:4096
	ds_read_b128 v[216:219], v141 offset:5120
	v_or_b32_e32 v159, s46, v6
	v_mul_u32_u24_e32 v6, 0x90, v6
	v_lshlrev_b32_e32 v158, 2, v7
	v_lshl_add_u64 v[144:145], v[2:3], 1, s[4:5]
	v_lshl_add_u64 v[146:147], v[4:5], 1, s[4:5]
	v_add3_u32 v160, 0, v6, v0
	v_mov_b32_e32 v2, v1
	v_mov_b32_e32 v3, v1
	v_mov_b32_e32 v4, v1
	v_mov_b32_e32 v5, v1
	v_mov_b32_e32 v6, v1
	v_mov_b32_e32 v7, v1
	v_mov_b32_e32 v8, v1
	v_mov_b32_e32 v9, v1
	v_mov_b32_e32 v10, v1
	v_mov_b32_e32 v11, v1
	v_mov_b32_e32 v12, v1
	v_mov_b32_e32 v13, v1
	v_mov_b32_e32 v14, v1
	v_mov_b32_e32 v15, v1
	v_mov_b32_e32 v16, v1
	v_mov_b32_e32 v17, v1
	v_mov_b32_e32 v18, v1
	v_mov_b32_e32 v19, v1
	v_mov_b32_e32 v20, v1
	v_mov_b32_e32 v21, v1
	v_mov_b32_e32 v22, v1
	v_mov_b32_e32 v23, v1
	v_mov_b32_e32 v24, v1
	v_mov_b32_e32 v25, v1
	v_mov_b32_e32 v26, v1
	v_mov_b32_e32 v27, v1
	v_mov_b32_e32 v28, v1
	v_mov_b32_e32 v29, v1
	v_mov_b32_e32 v30, v1
	v_mov_b32_e32 v31, v1
	s_lshl_b32 s48, s0, 2
	v_mov_b32_e32 v0, v1
	v_mov_b64_e32 v[32:33], v[30:31]
	s_lshl_b32 s47, s1, 13
	v_ashrrev_i32_e32 v139, 31, v138
	s_add_i32 s49, s48, 4
	s_or_b32 s50, s48, 3
	s_or_b32 s51, s46, 31
	s_mov_b32 s54, 0
	s_sub_i32 s55, 0, s48
	s_sub_i32 s56, 0, s8
	v_subrev_u32_e32 v161, s8, v158
	v_mov_b32_e32 v66, v1
	v_mov_b32_e32 v67, v1
	v_mov_b32_e32 v68, v1
	v_mov_b32_e32 v69, v1
	v_mov_b32_e32 v70, v1
	v_mov_b32_e32 v71, v1
	v_mov_b32_e32 v72, v1
	v_mov_b32_e32 v73, v1
	v_mov_b32_e32 v74, v1
	v_mov_b32_e32 v75, v1
	v_mov_b32_e32 v76, v1
	v_mov_b32_e32 v77, v1
	v_mov_b32_e32 v78, v1
	v_mov_b32_e32 v79, v1
	v_mov_b32_e32 v80, v1
	v_mov_b32_e32 v81, v1
	s_mov_b32 s57, 0xb000
	s_movk_i32 s58, 0x5800
	v_mov_b32_e32 v162, 0
	v_mov_b32_e32 v163, 0
	s_mov_b32 s0, 0
	s_mov_b32 s59, 0
	v_mov_b64_e32 v[30:31], v[28:29]
	v_mov_b64_e32 v[28:29], v[26:27]
	v_mov_b64_e32 v[26:27], v[24:25]
	v_mov_b64_e32 v[24:25], v[22:23]
	v_mov_b64_e32 v[22:23], v[20:21]
	v_mov_b64_e32 v[20:21], v[18:19]
	v_mov_b64_e32 v[18:19], v[16:17]
	v_mov_b64_e32 v[16:17], v[14:15]
	v_mov_b64_e32 v[14:15], v[12:13]
	v_mov_b64_e32 v[12:13], v[10:11]
	v_mov_b64_e32 v[10:11], v[8:9]
	v_mov_b64_e32 v[8:9], v[6:7]
	v_mov_b64_e32 v[6:7], v[4:5]
	v_mov_b64_e32 v[4:5], v[2:3]
	v_mov_b64_e32 v[2:3], v[0:1]
.LBB0_1037:
	s_add_i32 s1, s59, 3
	s_cmp_lt_u32 s1, s49
	s_cselect_b32 s1, s1, s50
	s_lshl_b32 s8, s1, 6
	v_add_u32_e32 v0, s8, v150
	v_mad_i64_i32 v[94:95], s[4:5], v0, s3, v[144:145]
	v_add_u32_e32 v0, s8, v151
	v_mad_i64_i32 v[96:97], s[4:5], v0, s3, v[146:147]
	v_lshl_add_u64 v[102:103], s[8:9], 1, v[142:143]
	global_load_dwordx4 v[98:101], v[94:95], off
	s_nop 0
	global_load_dwordx4 v[94:97], v[96:97], off
	s_add_i32 s62, s55, s59
	global_load_dwordx4 v[102:105], v[102:103], off
	s_cmp_lt_i32 s62, 0
	s_cselect_b64 s[18:19], -1, 0
	s_add_i32 s61, s56, s54
	s_cmp_le_i32 s61, s51
	s_cselect_b64 s[4:5], -1, 0
	s_or_b64 s[20:21], s[18:19], s[4:5]
	v_cndmask_b32_e64 v0, 0, 1, s[20:21]
	s_mov_b32 s60, s58
	v_cmp_ne_u32_e64 s[4:5], 1, v0
	s_andn2_b64 vcc, exec, s[20:21]
	s_mov_b32 s58, s0
	v_add_u32_e32 v248, s58, v160
	ds_read_b128 v[164:167], v248 offset:13312
	ds_read_b128 v[168:171], v248 offset:17920
	ds_read_b128 v[172:175], v248 offset:13344
	ds_read_b128 v[176:179], v248 offset:17952
	ds_read_b128 v[180:183], v248 offset:13376
	ds_read_b128 v[220:223], v248 offset:17984
	ds_read_b128 v[224:227], v248 offset:13408
	ds_read_b128 v[232:235], v248 offset:18016
	s_cbranch_vccnz .LBB0_1049
	s_cmp_lt_i32 s62, 0
	s_cbranch_scc1 .LBB0_1040
	v_add_u32_e32 v0, s54, v161
	v_add_u32_e32 v122, 32, v0
	v_cmp_le_i32_e32 vcc, v122, v159
	v_add_u32_e32 v122, 33, v0
	s_nop 0
	v_cndmask_b32_e32 v50, v149, v50, vcc
	v_cmp_lt_i32_e32 vcc, v0, v159
	s_nop 1
	v_cndmask_b32_e32 v35, v149, v35, vcc
	v_cmp_le_i32_e32 vcc, v0, v159
	s_nop 1
	v_cndmask_b32_e32 v34, v149, v34, vcc
	v_cmp_le_i32_e32 vcc, v122, v159
	v_add_u32_e32 v122, 2, v0
	s_nop 0
	v_cndmask_b32_e32 v51, v149, v51, vcc
	v_cmp_le_i32_e32 vcc, v122, v159
	v_add_u32_e32 v122, 34, v0
	s_nop 0
	v_cndmask_b32_e32 v36, v149, v36, vcc
	v_cmp_le_i32_e32 vcc, v122, v159
	v_add_u32_e32 v122, 3, v0
	s_nop 0
	v_cndmask_b32_e32 v52, v149, v52, vcc
	v_cmp_le_i32_e32 vcc, v122, v159
	v_add_u32_e32 v122, 35, v0
	s_nop 0
	v_cndmask_b32_e32 v37, v149, v37, vcc
	v_cmp_le_i32_e32 vcc, v122, v159
	v_add_u32_e32 v122, 8, v0
	s_nop 0
	v_cndmask_b32_e32 v53, v149, v53, vcc
	v_cmp_le_i32_e32 vcc, v122, v159
	v_add_u32_e32 v122, 40, v0
	s_nop 0
	v_cndmask_b32_e32 v38, v149, v38, vcc
	v_cmp_le_i32_e32 vcc, v122, v159
	v_add_u32_e32 v122, 9, v0
	s_nop 0
	v_cndmask_b32_e32 v54, v149, v54, vcc
	v_cmp_le_i32_e32 vcc, v122, v159
	v_add_u32_e32 v122, 41, v0
	s_nop 0
	v_cndmask_b32_e32 v39, v149, v39, vcc
	v_cmp_le_i32_e32 vcc, v122, v159
	v_add_u32_e32 v122, 10, v0
	s_nop 0
	v_cndmask_b32_e32 v55, v149, v55, vcc
	v_cmp_le_i32_e32 vcc, v122, v159
	v_add_u32_e32 v122, 42, v0
	s_nop 0
	v_cndmask_b32_e32 v40, v149, v40, vcc
	v_cmp_le_i32_e32 vcc, v122, v159
	v_add_u32_e32 v122, 11, v0
	s_nop 0
	v_cndmask_b32_e32 v56, v149, v56, vcc
	v_cmp_le_i32_e32 vcc, v122, v159
	v_add_u32_e32 v122, 43, v0
	s_nop 0
	v_cndmask_b32_e32 v41, v149, v41, vcc
	v_cmp_le_i32_e32 vcc, v122, v159
	v_add_u32_e32 v122, 16, v0
	s_nop 0
	v_cndmask_b32_e32 v57, v149, v57, vcc
	v_cmp_le_i32_e32 vcc, v122, v159
	v_add_u32_e32 v122, 48, v0
	s_nop 0
	v_cndmask_b32_e32 v42, v149, v42, vcc
	v_cmp_le_i32_e32 vcc, v122, v159
	v_add_u32_e32 v122, 17, v0
	s_nop 0
	v_cndmask_b32_e32 v58, v149, v58, vcc
	v_cmp_le_i32_e32 vcc, v122, v159
	v_add_u32_e32 v122, 49, v0
	s_nop 0
	v_cndmask_b32_e32 v43, v149, v43, vcc
	v_cmp_le_i32_e32 vcc, v122, v159
	v_add_u32_e32 v122, 18, v0
	s_nop 0
	v_cndmask_b32_e32 v59, v149, v59, vcc
	v_cmp_le_i32_e32 vcc, v122, v159
	v_add_u32_e32 v122, 50, v0
	s_nop 0
	v_cndmask_b32_e32 v44, v149, v44, vcc
	v_cmp_le_i32_e32 vcc, v122, v159
	v_add_u32_e32 v122, 19, v0
	s_nop 0
	v_cndmask_b32_e32 v60, v149, v60, vcc
	v_cmp_le_i32_e32 vcc, v122, v159
	v_add_u32_e32 v122, 51, v0
	s_nop 0
	v_cndmask_b32_e32 v45, v149, v45, vcc
	v_cmp_le_i32_e32 vcc, v122, v159
	v_add_u32_e32 v122, 24, v0
	s_nop 0
	v_cndmask_b32_e32 v61, v149, v61, vcc
	v_cmp_le_i32_e32 vcc, v122, v159
	v_add_u32_e32 v122, 56, v0
	s_nop 0
	v_cndmask_b32_e32 v46, v149, v46, vcc
	v_cmp_le_i32_e32 vcc, v122, v159
	v_add_u32_e32 v122, 25, v0
	s_nop 0
	v_cndmask_b32_e32 v62, v149, v62, vcc
	v_cmp_le_i32_e32 vcc, v122, v159
	v_add_u32_e32 v122, 57, v0
	s_nop 0
	v_cndmask_b32_e32 v47, v149, v47, vcc
	v_cmp_le_i32_e32 vcc, v122, v159
	v_add_u32_e32 v122, 26, v0
	s_nop 0
	v_cndmask_b32_e32 v63, v149, v63, vcc
	v_cmp_le_i32_e32 vcc, v122, v159
	v_add_u32_e32 v122, 58, v0
	s_nop 0
	v_cndmask_b32_e32 v48, v149, v48, vcc
	v_cmp_le_i32_e32 vcc, v122, v159
	v_add_u32_e32 v122, 27, v0
	v_add_u32_e32 v0, 59, v0
	v_cndmask_b32_e32 v64, v149, v64, vcc
	v_cmp_le_i32_e32 vcc, v122, v159
	s_nop 1
	v_cndmask_b32_e32 v49, v149, v49, vcc
	v_cmp_le_i32_e32 vcc, v0, v159
	s_nop 1
	v_cndmask_b32_e32 v65, v149, v65, vcc
.LBB0_1040:
	v_max3_f32 v0, v34, v35, v36
	v_max3_f32 v122, v50, v51, v52
	v_max3_f32 v0, v0, v37, v38
	v_max3_f32 v122, v122, v53, v54
	v_max3_f32 v0, v0, v39, v40
	v_max3_f32 v122, v122, v55, v56
	v_max3_f32 v0, v0, v41, v42
	v_max3_f32 v122, v122, v57, v58
	v_max3_f32 v0, v0, v43, v44
	v_max3_f32 v122, v122, v59, v60
	v_max3_f32 v0, v0, v45, v46
	v_max3_f32 v122, v122, v61, v62
	v_max_f32_e32 v123, v65, v65
	v_max_f32_e32 v124, v49, v49
	v_max3_f32 v0, v0, v47, v48
	v_max3_f32 v122, v122, v63, v64
	v_max_f32_e32 v123, v124, v123
	v_max3_f32 v0, v0, v122, v123
	s_cmp_lg_u32 s54, 0
	s_cselect_b64 s[20:21], -1, 0
	s_cmp_eq_u32 s54, 0
	s_cbranch_scc1 .Lmla_a_xchg
	v_cmp_lt_f32_e32 vcc, s35, v0
	s_cbranch_vccz .LBB0_1044
.Lmla_a_xchg:
	v_and_b32_e32 v123, 64, v148
	v_xor_b32_e32 v122, 32, v148
	v_add_u32_e32 v123, 64, v123
	v_cmp_lt_i32_e32 vcc, v122, v123
	s_nop 1
	v_cndmask_b32_e32 v122, v148, v122, vcc
	v_lshlrev_b32_e32 v122, 2, v122
	ds_bpermute_b32 v122, v122, v0
	s_cmp_eq_u32 s54, 0
	s_waitcnt lgkmcnt(0)
	v_max_f32_e32 v122, v122, v122
	v_max_f32_e32 v0, v0, v122
	s_cbranch_scc1 .LBB0_1043
	v_max_f32_e32 v0, v0, v0
	v_max_f32_e32 v0, 0, v0

.LBB0_1048:
	v_exp_f32_e32 v34, v34
	v_exp_f32_e32 v50, v50
	v_exp_f32_e32 v35, v35
	v_exp_f32_e32 v51, v51
	v_exp_f32_e32 v42, v42
	v_exp_f32_e32 v58, v58
	v_exp_f32_e32 v43, v43
	v_exp_f32_e32 v59, v59
	v_exp_f32_e32 v36, v36
	v_exp_f32_e32 v52, v52
	v_exp_f32_e32 v37, v37
	v_exp_f32_e32 v53, v53
	v_exp_f32_e32 v44, v44
	v_exp_f32_e32 v60, v60
	v_exp_f32_e32 v45, v45
	v_exp_f32_e32 v61, v61
	v_exp_f32_e32 v38, v38
	v_exp_f32_e32 v54, v54
	v_exp_f32_e32 v39, v39
	v_exp_f32_e32 v55, v55
	v_exp_f32_e32 v46, v46
	v_exp_f32_e32 v62, v62
	v_exp_f32_e32 v47, v47
	v_exp_f32_e32 v63, v63
	v_exp_f32_e32 v40, v40
	v_exp_f32_e32 v56, v56
	v_exp_f32_e32 v41, v41
	v_exp_f32_e32 v57, v57
	v_exp_f32_e32 v48, v48
	v_exp_f32_e32 v64, v64
	v_exp_f32_e32 v49, v49
	v_exp_f32_e32 v65, v65
	v_pk_add_f32 v[122:123], v[34:35], v[50:51]
	v_pk_add_f32 v[124:125], v[36:37], v[52:53]
	v_pk_add_f32 v[126:127], v[38:39], v[54:55]
	v_pk_add_f32 v[128:129], v[40:41], v[56:57]
	v_pk_add_f32 v[130:131], v[42:43], v[58:59]
	v_pk_add_f32 v[132:133], v[44:45], v[60:61]
	v_pk_add_f32 v[134:135], v[46:47], v[62:63]
	v_pk_add_f32 v[136:137], v[48:49], v[64:65]
	v_pk_add_f32 v[122:123], v[122:123], v[124:125]
	v_pk_add_f32 v[126:127], v[126:127], v[128:129]
	v_pk_add_f32 v[130:131], v[130:131], v[132:133]
	v_pk_add_f32 v[134:135], v[134:135], v[136:137]
	v_pk_add_f32 v[122:123], v[122:123], v[126:127]
	v_pk_add_f32 v[130:131], v[130:131], v[134:135]
	v_pk_add_f32 v[122:123], v[122:123], v[130:131]
	v_add_f32_e32 v0, v122, v123
	v_cvt_pk_bf16_f32 v122, v34, v35
	v_cvt_pk_bf16_f32 v123, v36, v37
	v_cvt_pk_bf16_f32 v124, v38, v39
	v_cvt_pk_bf16_f32 v125, v40, v41
	v_cvt_pk_bf16_f32 v126, v42, v43
	v_cvt_pk_bf16_f32 v127, v44, v45
	v_cvt_pk_bf16_f32 v128, v46, v47
	v_cvt_pk_bf16_f32 v129, v48, v49
	v_cvt_pk_bf16_f32 v130, v50, v51
	v_cvt_pk_bf16_f32 v131, v52, v53
	v_cvt_pk_bf16_f32 v132, v54, v55
	v_cvt_pk_bf16_f32 v133, v56, v57
	v_cvt_pk_bf16_f32 v134, v58, v59
	v_cvt_pk_bf16_f32 v135, v60, v61
	v_cvt_pk_bf16_f32 v136, v62, v63
	v_cvt_pk_bf16_f32 v137, v64, v65
	v_add_f32_e32 v162, v162, v0
.LBB0_1049:
	s_waitcnt lgkmcnt(0)
	s_barrier
	s_and_b64 vcc, exec, s[4:5]
	s_cbranch_vccnz .LBB0_1051
	v_add_u32_e32 v249, s60, v157
	ds_read_b128 v[236:239], v249
	ds_read_b128 v[240:243], v249 offset:6656
	ds_read_b128 v[244:247], v249 offset:32
	v_mfma_f32_32x32x16_bf16 v[2:17], v[164:167], v[122:125], v[2:17]
	ds_read_b128 v[164:167], v249 offset:6688
	v_mfma_f32_32x32x16_bf16 v[18:33], v[168:171], v[122:125], v[18:33]
	ds_read_b128 v[168:171], v249 offset:64
	v_mfma_f32_32x32x16_bf16 v[2:17], v[172:175], v[126:129], v[2:17]
	ds_read_b128 v[172:175], v249 offset:6720
	v_mfma_f32_32x32x16_bf16 v[18:33], v[176:179], v[126:129], v[18:33]
	ds_read_b128 v[176:179], v249 offset:96
	v_mfma_f32_32x32x16_bf16 v[2:17], v[180:183], v[130:133], v[2:17]
	ds_read_b128 v[180:183], v249 offset:6752
	v_mfma_f32_32x32x16_bf16 v[18:33], v[220:223], v[130:133], v[18:33]
	ds_read_b128 v[220:223], v249 offset:128
	v_mfma_f32_32x32x16_bf16 v[2:17], v[224:227], v[134:137], v[2:17]
	ds_read_b128 v[224:227], v249 offset:6784
	v_mfma_f32_32x32x16_bf16 v[18:33], v[232:235], v[134:137], v[18:33]
	ds_read_b128 v[232:235], v249 offset:160
.LBB0_1051:
	s_add_i32 s0, s59, 1
	s_cmp_lt_u32 s0, s49
	s_cselect_b64 s[0:1], -1, 0
	s_add_i32 s4, s61, 33
	s_cmp_le_i32 s4, s46
	s_cselect_b64 s[4:5], -1, 0
	s_or_b64 s[4:5], s[18:19], s[4:5]
	s_and_b64 s[0:1], s[0:1], s[4:5]
	s_andn2_b64 vcc, exec, s[0:1]
	s_cbranch_vccnz .LBB0_1053
	s_waitcnt lgkmcnt(10)
	v_mfma_f32_32x32x16_bf16 v[34:49], v[236:239], v[196:199], v[66:81]
	ds_read_b128 v[236:239], v249 offset:6816
	s_waitcnt lgkmcnt(10)
	v_mfma_f32_32x32x16_bf16 v[50:65], v[240:243], v[196:199], v[66:81]
	s_waitcnt lgkmcnt(9)
	v_mfma_f32_32x32x16_bf16 v[34:49], v[244:247], v[200:203], v[34:49]
	s_waitcnt lgkmcnt(8)
	v_mfma_f32_32x32x16_bf16 v[50:65], v[164:167], v[200:203], v[50:65]
	s_waitcnt lgkmcnt(7)
	v_mfma_f32_32x32x16_bf16 v[34:49], v[168:171], v[204:207], v[34:49]
	s_waitcnt lgkmcnt(6)
	v_mfma_f32_32x32x16_bf16 v[50:65], v[172:175], v[204:207], v[50:65]
	s_waitcnt lgkmcnt(5)
	v_mfma_f32_32x32x16_bf16 v[34:49], v[176:179], v[208:211], v[34:49]
	s_waitcnt lgkmcnt(4)
	v_mfma_f32_32x32x16_bf16 v[50:65], v[180:183], v[208:211], v[50:65]
	s_waitcnt lgkmcnt(3)
	v_mfma_f32_32x32x16_bf16 v[34:49], v[220:223], v[212:215], v[34:49]
	s_waitcnt lgkmcnt(2)
	v_mfma_f32_32x32x16_bf16 v[50:65], v[224:227], v[212:215], v[50:65]
	s_waitcnt lgkmcnt(1)
	v_mfma_f32_32x32x16_bf16 v[34:49], v[232:235], v[216:219], v[34:49]
	s_waitcnt lgkmcnt(0)
	v_mfma_f32_32x32x16_bf16 v[50:65], v[236:239], v[216:219], v[50:65]
.LBB0_1053:
	s_add_i32 s0, s57, 0
	v_add3_u32 v0, s0, v152, v153
	s_waitcnt vmcnt(4)
	ds_write_b128 v0, v[86:89]
	v_add3_u32 v0, s0, v154, v155
	s_waitcnt vmcnt(3)
	ds_write_b128 v0, v[90:93]
	v_add3_u32 v0, s0, v156, v140
	s_add_i32 s0, s59, 4
	s_cmp_lt_u32 s59, s48
	s_cselect_b32 s0, s0, s50
	s_lshl_b32 s8, s0, 6
	ds_write_b128 v0, v[82:85] offset:13312
	v_add_u32_e32 v0, s8, v150
	s_waitcnt lgkmcnt(0)
	s_barrier
	v_mad_i64_i32 v[82:83], s[0:1], v0, s3, v[144:145]
	v_add_u32_e32 v0, s8, v151
	v_mad_i64_i32 v[84:85], s[0:1], v0, s3, v[146:147]
	global_load_dwordx4 v[86:89], v[82:83], off
	global_load_dwordx4 v[90:93], v[84:85], off
	v_lshl_add_u64 v[82:83], s[8:9], 1, v[142:143]
	global_load_dwordx4 v[82:85], v[82:83], off
	v_add_u32_e32 v248, s60, v160
	ds_read_b128 v[164:167], v248 offset:13312
	ds_read_b128 v[168:171], v248 offset:17920
	ds_read_b128 v[172:175], v248 offset:13344
	ds_read_b128 v[176:179], v248 offset:17952
	ds_read_b128 v[180:183], v248 offset:13376
	ds_read_b128 v[220:223], v248 offset:17984
	ds_read_b128 v[224:227], v248 offset:13408
	ds_read_b128 v[232:235], v248 offset:18016
	s_add_i32 s62, s62, 1
	s_cmp_lt_i32 s62, 0
	s_cselect_b64 s[0:1], -1, 0
	s_add_i32 s4, s61, 64
	s_cmp_le_i32 s4, s51
	s_cselect_b64 s[4:5], -1, 0
	s_or_b64 s[0:1], s[0:1], s[4:5]
	v_cndmask_b32_e64 v0, 0, 1, s[0:1]
	v_cmp_ne_u32_e64 s[4:5], 1, v0
	s_andn2_b64 vcc, exec, s[0:1]
	s_cbranch_vccnz .LBB0_1059
	s_cmp_lt_i32 s62, 0
	s_cbranch_scc1 .LBB0_1056
	v_add_u32_e32 v0, s54, v161
	v_add_u32_e32 v107, 0x60, v0
	v_add_u32_e32 v106, 64, v0
	v_cmp_le_i32_e32 vcc, v107, v159
	s_nop 1
	v_cndmask_b32_e32 v50, v149, v50, vcc
	v_cmp_lt_i32_e32 vcc, v106, v159
	s_nop 1
	v_cndmask_b32_e32 v35, v149, v35, vcc
	v_cmp_le_i32_e32 vcc, v106, v159
	v_add_u32_e32 v106, 0x61, v0
	s_nop 0
	v_cndmask_b32_e32 v34, v149, v34, vcc
	v_cmp_le_i32_e32 vcc, v106, v159
	v_add_u32_e32 v106, 0x42, v0
	s_nop 0
	v_cndmask_b32_e32 v51, v149, v51, vcc
	v_cmp_le_i32_e32 vcc, v106, v159
	v_add_u32_e32 v106, 0x62, v0
	s_nop 0
	v_cndmask_b32_e32 v36, v149, v36, vcc
	v_cmp_le_i32_e32 vcc, v106, v159
	v_add_u32_e32 v106, 0x43, v0
	s_nop 0
	v_cndmask_b32_e32 v52, v149, v52, vcc
	v_cmp_le_i32_e32 vcc, v106, v159
	v_add_u32_e32 v106, 0x63, v0
	s_nop 0
	v_cndmask_b32_e32 v37, v149, v37, vcc
	v_cmp_le_i32_e32 vcc, v106, v159
	v_add_u32_e32 v106, 0x48, v0
	s_nop 0
	v_cndmask_b32_e32 v53, v149, v53, vcc
	v_cmp_le_i32_e32 vcc, v106, v159
	v_add_u32_e32 v106, 0x68, v0
	s_nop 0
	v_cndmask_b32_e32 v38, v149, v38, vcc
	v_cmp_le_i32_e32 vcc, v106, v159
	v_add_u32_e32 v106, 0x49, v0
	s_nop 0
	v_cndmask_b32_e32 v54, v149, v54, vcc
	v_cmp_le_i32_e32 vcc, v106, v159
	v_add_u32_e32 v106, 0x69, v0
	s_nop 0
	v_cndmask_b32_e32 v39, v149, v39, vcc
	v_cmp_le_i32_e32 vcc, v106, v159
	v_add_u32_e32 v106, 0x4a, v0
	s_nop 0
	v_cndmask_b32_e32 v55, v149, v55, vcc
	v_cmp_le_i32_e32 vcc, v106, v159
	v_add_u32_e32 v106, 0x6a, v0
	s_nop 0
	v_cndmask_b32_e32 v40, v149, v40, vcc
	v_cmp_le_i32_e32 vcc, v106, v159
	v_add_u32_e32 v106, 0x4b, v0
	s_nop 0
	v_cndmask_b32_e32 v56, v149, v56, vcc
	v_cmp_le_i32_e32 vcc, v106, v159
	v_add_u32_e32 v106, 0x6b, v0
	s_nop 0
	v_cndmask_b32_e32 v41, v149, v41, vcc
	v_cmp_le_i32_e32 vcc, v106, v159
	v_add_u32_e32 v106, 0x50, v0
	s_nop 0
	v_cndmask_b32_e32 v57, v149, v57, vcc
	v_cmp_le_i32_e32 vcc, v106, v159
	v_add_u32_e32 v106, 0x70, v0
	s_nop 0
	v_cndmask_b32_e32 v42, v149, v42, vcc
	v_cmp_le_i32_e32 vcc, v106, v159
	v_add_u32_e32 v106, 0x51, v0
	s_nop 0
	v_cndmask_b32_e32 v58, v149, v58, vcc
	v_cmp_le_i32_e32 vcc, v106, v159
	v_add_u32_e32 v106, 0x71, v0
	s_nop 0
	v_cndmask_b32_e32 v43, v149, v43, vcc
	v_cmp_le_i32_e32 vcc, v106, v159
	v_add_u32_e32 v106, 0x52, v0
	s_nop 0
	v_cndmask_b32_e32 v59, v149, v59, vcc
	v_cmp_le_i32_e32 vcc, v106, v159
	v_add_u32_e32 v106, 0x72, v0
	s_nop 0
	v_cndmask_b32_e32 v44, v149, v44, vcc
	v_cmp_le_i32_e32 vcc, v106, v159
	v_add_u32_e32 v106, 0x53, v0
	s_nop 0
	v_cndmask_b32_e32 v60, v149, v60, vcc
	v_cmp_le_i32_e32 vcc, v106, v159
	v_add_u32_e32 v106, 0x73, v0
	s_nop 0
	v_cndmask_b32_e32 v45, v149, v45, vcc
	v_cmp_le_i32_e32 vcc, v106, v159
	v_add_u32_e32 v106, 0x58, v0
	s_nop 0
	v_cndmask_b32_e32 v61, v149, v61, vcc
	v_cmp_le_i32_e32 vcc, v106, v159
	v_add_u32_e32 v106, 0x78, v0
	s_nop 0
	v_cndmask_b32_e32 v46, v149, v46, vcc
	v_cmp_le_i32_e32 vcc, v106, v159
	v_add_u32_e32 v106, 0x59, v0
	s_nop 0
	v_cndmask_b32_e32 v62, v149, v62, vcc
	v_cmp_le_i32_e32 vcc, v106, v159
	v_add_u32_e32 v106, 0x79, v0
	s_nop 0
	v_cndmask_b32_e32 v47, v149, v47, vcc
	v_cmp_le_i32_e32 vcc, v106, v159
	v_add_u32_e32 v106, 0x5a, v0
	s_nop 0
	v_cndmask_b32_e32 v63, v149, v63, vcc
	v_cmp_le_i32_e32 vcc, v106, v159
	v_add_u32_e32 v106, 0x7a, v0
	s_nop 0
	v_cndmask_b32_e32 v48, v149, v48, vcc
	v_cmp_le_i32_e32 vcc, v106, v159
	v_add_u32_e32 v106, 0x5b, v0
	v_add_u32_e32 v0, 0x7b, v0
	v_cndmask_b32_e32 v64, v149, v64, vcc
	v_cmp_le_i32_e32 vcc, v106, v159
	s_nop 1
	v_cndmask_b32_e32 v49, v149, v49, vcc
	v_cmp_le_i32_e32 vcc, v0, v159
	s_nop 1
	v_cndmask_b32_e32 v65, v149, v65, vcc
.LBB0_1056:
	v_max3_f32 v0, v34, v35, v36
	v_max3_f32 v106, v50, v51, v52
	v_max3_f32 v0, v0, v37, v38
	v_max3_f32 v106, v106, v53, v54
	v_max3_f32 v0, v0, v39, v40
	v_max3_f32 v106, v106, v55, v56
	v_max3_f32 v0, v0, v41, v42
	v_max3_f32 v106, v106, v57, v58
	v_max3_f32 v0, v0, v43, v44
	v_max3_f32 v106, v106, v59, v60
	v_max3_f32 v0, v0, v45, v46
	v_max3_f32 v106, v106, v61, v62
	v_max_f32_e32 v107, v65, v65
	v_max_f32_e32 v108, v49, v49
	v_max3_f32 v0, v0, v47, v48
	v_max3_f32 v106, v106, v63, v64
	v_max_f32_e32 v107, v108, v107
	v_max3_f32 v0, v0, v106, v107
	v_cmp_lt_f32_e32 vcc, s35, v0
	s_cbranch_vccz .LBB0_1058
	v_and_b32_e32 v107, 64, v148
	v_xor_b32_e32 v106, 32, v148
	v_add_u32_e32 v107, 64, v107
	v_cmp_lt_i32_e32 vcc, v106, v107
	s_nop 1
	v_cndmask_b32_e32 v106, v148, v106, vcc
	v_lshlrev_b32_e32 v106, 2, v106
	ds_bpermute_b32 v106, v106, v0
	s_waitcnt lgkmcnt(0)
	v_max_f32_e32 v106, v106, v106
	v_max_f32_e32 v0, v0, v106
	v_max_f32_e32 v0, v0, v0
	v_max_f32_e32 v66, 0, v0
	v_exp_f32_e64 v0, -v66
	v_add_f32_e32 v163, v163, v66
	v_sub_f32_e32 v49, v49, v66
	v_sub_f32_e32 v48, v48, v66
	v_sub_f32_e32 v47, v47, v66
	v_sub_f32_e32 v46, v46, v66
	v_sub_f32_e32 v45, v45, v66
	v_sub_f32_e32 v44, v44, v66
	v_sub_f32_e32 v43, v43, v66
	v_sub_f32_e32 v42, v42, v66
	v_sub_f32_e32 v41, v41, v66
	v_sub_f32_e32 v40, v40, v66
	v_sub_f32_e32 v39, v39, v66
	v_sub_f32_e32 v38, v38, v66
	v_sub_f32_e32 v37, v37, v66
	v_sub_f32_e32 v36, v36, v66
	v_sub_f32_e32 v35, v35, v66
	v_sub_f32_e32 v34, v34, v66
	v_sub_f32_e32 v65, v65, v66
	v_sub_f32_e32 v64, v64, v66
	v_sub_f32_e32 v63, v63, v66
	v_sub_f32_e32 v62, v62, v66
	v_sub_f32_e32 v61, v61, v66
	v_sub_f32_e32 v60, v60, v66
	v_sub_f32_e32 v59, v59, v66
	v_sub_f32_e32 v58, v58, v66
	v_sub_f32_e32 v57, v57, v66
	v_sub_f32_e32 v56, v56, v66
	v_sub_f32_e32 v55, v55, v66
	v_sub_f32_e32 v54, v54, v66
	v_sub_f32_e32 v53, v53, v66
	v_sub_f32_e32 v52, v52, v66
	v_sub_f32_e32 v51, v51, v66
	v_sub_f32_e32 v50, v50, v66
	v_xor_b32_e32 v66, 0x80000000, v163
	v_mov_b32_e32 v67, v66
	v_mov_b32_e32 v68, v66
	v_mov_b32_e32 v69, v66
	v_mov_b32_e32 v70, v66
	v_mov_b32_e32 v71, v66
	v_mov_b32_e32 v72, v66
	v_mov_b32_e32 v73, v66
	v_mov_b32_e32 v74, v66
	v_mov_b32_e32 v75, v66
	v_mov_b32_e32 v76, v66
	v_mov_b32_e32 v77, v66
	v_mov_b32_e32 v78, v66
	v_mov_b32_e32 v79, v66
	v_mov_b32_e32 v80, v66
	v_mov_b32_e32 v81, v66
	v_pk_mul_f32 v[32:33], v[32:33], v[0:1] op_sel_hi:[1,0]
	v_pk_mul_f32 v[30:31], v[30:31], v[0:1] op_sel_hi:[1,0]
	v_pk_mul_f32 v[28:29], v[28:29], v[0:1] op_sel_hi:[1,0]
	v_pk_mul_f32 v[26:27], v[26:27], v[0:1] op_sel_hi:[1,0]
	v_pk_mul_f32 v[24:25], v[24:25], v[0:1] op_sel_hi:[1,0]
	v_pk_mul_f32 v[22:23], v[22:23], v[0:1] op_sel_hi:[1,0]
	v_pk_mul_f32 v[20:21], v[20:21], v[0:1] op_sel_hi:[1,0]
	v_pk_mul_f32 v[18:19], v[18:19], v[0:1] op_sel_hi:[1,0]
	v_pk_mul_f32 v[16:17], v[16:17], v[0:1] op_sel_hi:[1,0]
	v_pk_mul_f32 v[14:15], v[14:15], v[0:1] op_sel_hi:[1,0]
	v_pk_mul_f32 v[12:13], v[12:13], v[0:1] op_sel_hi:[1,0]
	v_pk_mul_f32 v[10:11], v[10:11], v[0:1] op_sel_hi:[1,0]
	v_pk_mul_f32 v[8:9], v[8:9], v[0:1] op_sel_hi:[1,0]
	v_pk_mul_f32 v[6:7], v[6:7], v[0:1] op_sel_hi:[1,0]
	v_pk_mul_f32 v[4:5], v[4:5], v[0:1] op_sel_hi:[1,0]
	v_pk_mul_f32 v[2:3], v[2:3], v[0:1] op_sel_hi:[1,0]
	v_mul_f32_e32 v162, v162, v0
.LBB0_1058:
	v_exp_f32_e32 v34, v34
	v_exp_f32_e32 v50, v50
	v_exp_f32_e32 v35, v35
	v_exp_f32_e32 v51, v51
	v_exp_f32_e32 v42, v42
	v_exp_f32_e32 v58, v58
	v_exp_f32_e32 v43, v43
	v_exp_f32_e32 v59, v59
	v_exp_f32_e32 v36, v36
	v_exp_f32_e32 v52, v52
	v_exp_f32_e32 v37, v37
	v_exp_f32_e32 v53, v53
	v_exp_f32_e32 v44, v44
	v_exp_f32_e32 v60, v60
	v_exp_f32_e32 v45, v45
	v_exp_f32_e32 v61, v61
	v_exp_f32_e32 v38, v38
	v_exp_f32_e32 v54, v54
	v_exp_f32_e32 v39, v39
	v_exp_f32_e32 v55, v55
	v_exp_f32_e32 v46, v46
	v_exp_f32_e32 v62, v62
	v_exp_f32_e32 v47, v47
	v_exp_f32_e32 v63, v63
	v_exp_f32_e32 v40, v40
	v_exp_f32_e32 v56, v56
	v_exp_f32_e32 v41, v41
	v_exp_f32_e32 v57, v57
	v_exp_f32_e32 v48, v48
	v_exp_f32_e32 v64, v64
	v_exp_f32_e32 v49, v49
	v_exp_f32_e32 v65, v65
	v_pk_add_f32 v[106:107], v[34:35], v[50:51]
	v_pk_add_f32 v[108:109], v[36:37], v[52:53]
	v_pk_add_f32 v[110:111], v[38:39], v[54:55]
	v_pk_add_f32 v[112:113], v[40:41], v[56:57]
	v_pk_add_f32 v[114:115], v[42:43], v[58:59]
	v_pk_add_f32 v[116:117], v[44:45], v[60:61]
	v_pk_add_f32 v[118:119], v[46:47], v[62:63]
	v_pk_add_f32 v[120:121], v[48:49], v[64:65]
	v_pk_add_f32 v[106:107], v[106:107], v[108:109]
	v_pk_add_f32 v[110:111], v[110:111], v[112:113]
	v_pk_add_f32 v[114:115], v[114:115], v[116:117]
	v_pk_add_f32 v[118:119], v[118:119], v[120:121]
	v_pk_add_f32 v[106:107], v[106:107], v[110:111]
	v_pk_add_f32 v[114:115], v[114:115], v[118:119]
	v_pk_add_f32 v[106:107], v[106:107], v[114:115]
	v_add_f32_e32 v0, v106, v107
	v_cvt_pk_bf16_f32 v106, v34, v35
	v_cvt_pk_bf16_f32 v107, v36, v37
	v_cvt_pk_bf16_f32 v108, v38, v39
	v_cvt_pk_bf16_f32 v109, v40, v41
	v_cvt_pk_bf16_f32 v110, v42, v43
	v_cvt_pk_bf16_f32 v111, v44, v45
	v_cvt_pk_bf16_f32 v112, v46, v47
	v_cvt_pk_bf16_f32 v113, v48, v49
	v_cvt_pk_bf16_f32 v114, v50, v51
	v_cvt_pk_bf16_f32 v115, v52, v53
	v_cvt_pk_bf16_f32 v116, v54, v55
	v_cvt_pk_bf16_f32 v117, v56, v57
	v_cvt_pk_bf16_f32 v118, v58, v59
	v_cvt_pk_bf16_f32 v119, v60, v61
	v_cvt_pk_bf16_f32 v120, v62, v63
	v_cvt_pk_bf16_f32 v121, v64, v65
	v_add_f32_e32 v162, v162, v0
.LBB0_1059:
	s_waitcnt lgkmcnt(0)
	s_barrier
	s_and_b64 vcc, exec, s[4:5]
	s_cbranch_vccnz .LBB0_1061
	v_add_u32_e32 v249, s57, v157
	ds_read_b128 v[236:239], v249
	ds_read_b128 v[240:243], v249 offset:6656
	ds_read_b128 v[244:247], v249 offset:32
	v_mfma_f32_32x32x16_bf16 v[2:17], v[164:167], v[106:109], v[2:17]
	ds_read_b128 v[164:167], v249 offset:6688
	v_mfma_f32_32x32x16_bf16 v[18:33], v[168:171], v[106:109], v[18:33]
	ds_read_b128 v[168:171], v249 offset:64
	v_mfma_f32_32x32x16_bf16 v[2:17], v[172:175], v[110:113], v[2:17]
	ds_read_b128 v[172:175], v249 offset:6720
	v_mfma_f32_32x32x16_bf16 v[18:33], v[176:179], v[110:113], v[18:33]
	ds_read_b128 v[176:179], v249 offset:96
	v_mfma_f32_32x32x16_bf16 v[2:17], v[180:183], v[114:117], v[2:17]
	ds_read_b128 v[180:183], v249 offset:6752
	v_mfma_f32_32x32x16_bf16 v[18:33], v[220:223], v[114:117], v[18:33]
	ds_read_b128 v[220:223], v249 offset:128
	v_mfma_f32_32x32x16_bf16 v[2:17], v[224:227], v[118:121], v[2:17]
	ds_read_b128 v[224:227], v249 offset:6784
	v_mfma_f32_32x32x16_bf16 v[18:33], v[232:235], v[118:121], v[18:33]
	ds_read_b128 v[232:235], v249 offset:160
.LBB0_1061:
	s_add_i32 s59, s59, 2
	s_cmp_ge_u32 s59, s49
	s_cselect_b64 s[4:5], -1, 0
	s_cmp_lt_u32 s59, s49
	s_cselect_b64 s[0:1], -1, 0
	s_cmp_lt_i32 s62, -1
	s_cselect_b64 s[18:19], -1, 0
	s_addk_i32 s61, 0x61
	s_cmp_le_i32 s61, s46
	s_cselect_b64 s[20:21], -1, 0
	s_or_b64 s[18:19], s[18:19], s[20:21]
	s_and_b64 s[0:1], s[0:1], s[18:19]
	s_andn2_b64 vcc, exec, s[0:1]
	s_cbranch_vccnz .LBB0_1063
	s_waitcnt lgkmcnt(10)
	v_mfma_f32_32x32x16_bf16 v[34:49], v[236:239], v[196:199], v[66:81]
	ds_read_b128 v[236:239], v249 offset:6816
	s_waitcnt lgkmcnt(10)
	v_mfma_f32_32x32x16_bf16 v[50:65], v[240:243], v[196:199], v[66:81]
	s_waitcnt lgkmcnt(9)
	v_mfma_f32_32x32x16_bf16 v[34:49], v[244:247], v[200:203], v[34:49]
	s_waitcnt lgkmcnt(8)
	v_mfma_f32_32x32x16_bf16 v[50:65], v[164:167], v[200:203], v[50:65]
	s_waitcnt lgkmcnt(7)
	v_mfma_f32_32x32x16_bf16 v[34:49], v[168:171], v[204:207], v[34:49]
	s_waitcnt lgkmcnt(6)
	v_mfma_f32_32x32x16_bf16 v[50:65], v[172:175], v[204:207], v[50:65]
	s_waitcnt lgkmcnt(5)
	v_mfma_f32_32x32x16_bf16 v[34:49], v[176:179], v[208:211], v[34:49]
	s_waitcnt lgkmcnt(4)
	v_mfma_f32_32x32x16_bf16 v[50:65], v[180:183], v[208:211], v[50:65]
	s_waitcnt lgkmcnt(3)
	v_mfma_f32_32x32x16_bf16 v[34:49], v[220:223], v[212:215], v[34:49]
	s_waitcnt lgkmcnt(2)
	v_mfma_f32_32x32x16_bf16 v[50:65], v[224:227], v[212:215], v[50:65]
	s_waitcnt lgkmcnt(1)
	v_mfma_f32_32x32x16_bf16 v[34:49], v[232:235], v[216:219], v[34:49]
	s_waitcnt lgkmcnt(0)
	v_mfma_f32_32x32x16_bf16 v[50:65], v[236:239], v[216:219], v[50:65]

.LBB0_1075:
	v_max3_f32 v0, v80, v81, v82
	v_max3_f32 v14, v96, v97, v98
	v_max3_f32 v0, v0, v83, v84
	v_max3_f32 v14, v14, v99, v100
	v_max3_f32 v0, v0, v85, v86
	v_max3_f32 v14, v14, v101, v102
	v_max3_f32 v0, v0, v87, v88
	v_max3_f32 v14, v14, v103, v104
	v_max3_f32 v0, v0, v89, v90
	v_max3_f32 v14, v14, v105, v106
	v_max3_f32 v0, v0, v91, v92
	v_max3_f32 v14, v14, v107, v108
	v_max_f32_e32 v15, v111, v111
	v_max_f32_e32 v156, v95, v95
	v_max3_f32 v0, v0, v93, v94
	v_max3_f32 v14, v14, v109, v110
	v_max_f32_e32 v15, v156, v15
	v_max3_f32 v0, v0, v14, v15
	s_cmp_lg_u32 s47, 0
	s_cselect_b64 s[18:19], -1, 0
	s_cmp_eq_u32 s47, 0
	s_cbranch_scc1 .Ldiff_a_xchg
	v_cmp_lt_f32_e32 vcc, s33, v0
	s_cbranch_vccz .LBB0_1079
.Ldiff_a_xchg:
	ds_bpermute_b32 v14, v184, v0
	s_cmp_eq_u32 s47, 0
	s_waitcnt lgkmcnt(0)
	v_max_f32_e32 v14, v14, v14
	v_max_f32_e32 v0, v0, v14
	s_cbranch_scc1 .LBB0_1078
	v_max_f32_e32 v0, v0, v0
	v_max_f32_e32 v0, 0, v0

.LBB0_1083:
	v_exp_f32_e32 v80, v80
	v_exp_f32_e32 v96, v96
	v_exp_f32_e32 v81, v81
	v_exp_f32_e32 v97, v97
	v_exp_f32_e32 v88, v88
	v_exp_f32_e32 v104, v104
	v_exp_f32_e32 v89, v89
	v_exp_f32_e32 v105, v105
	v_exp_f32_e32 v82, v82
	v_exp_f32_e32 v98, v98
	v_exp_f32_e32 v83, v83
	v_exp_f32_e32 v99, v99
	v_exp_f32_e32 v90, v90
	v_exp_f32_e32 v106, v106
	v_exp_f32_e32 v91, v91
	v_exp_f32_e32 v107, v107
	v_exp_f32_e32 v84, v84
	v_exp_f32_e32 v100, v100
	v_exp_f32_e32 v85, v85
	v_exp_f32_e32 v101, v101
	v_exp_f32_e32 v92, v92
	v_exp_f32_e32 v108, v108
	v_exp_f32_e32 v93, v93
	v_exp_f32_e32 v109, v109
	v_exp_f32_e32 v86, v86
	v_exp_f32_e32 v102, v102
	v_exp_f32_e32 v87, v87
	v_exp_f32_e32 v103, v103
	v_exp_f32_e32 v94, v94
	v_exp_f32_e32 v110, v110
	v_exp_f32_e32 v95, v95
	v_exp_f32_e32 v111, v111
	v_pk_add_f32 v[156:157], v[80:81], v[96:97]
	v_pk_add_f32 v[158:159], v[82:83], v[98:99]
	v_pk_add_f32 v[160:161], v[84:85], v[100:101]
	v_pk_add_f32 v[162:163], v[86:87], v[102:103]
	v_pk_add_f32 v[164:165], v[88:89], v[104:105]
	v_pk_add_f32 v[166:167], v[90:91], v[106:107]
	v_pk_add_f32 v[168:169], v[92:93], v[108:109]
	v_pk_add_f32 v[170:171], v[94:95], v[110:111]
	v_pk_add_f32 v[156:157], v[156:157], v[158:159]
	v_pk_add_f32 v[160:161], v[160:161], v[162:163]
	v_pk_add_f32 v[164:165], v[164:165], v[166:167]
	v_pk_add_f32 v[168:169], v[168:169], v[170:171]
	v_pk_add_f32 v[156:157], v[156:157], v[160:161]
	v_pk_add_f32 v[164:165], v[164:165], v[168:169]
	v_pk_add_f32 v[156:157], v[156:157], v[164:165]
	v_add_f32_e32 v0, v156, v157
	v_cvt_pk_bf16_f32 v156, v80, v81
	v_cvt_pk_bf16_f32 v157, v82, v83
	v_cvt_pk_bf16_f32 v158, v84, v85
	v_cvt_pk_bf16_f32 v159, v86, v87
	v_cvt_pk_bf16_f32 v160, v88, v89
	v_cvt_pk_bf16_f32 v161, v90, v91
	v_cvt_pk_bf16_f32 v162, v92, v93
	v_cvt_pk_bf16_f32 v163, v94, v95
	v_cvt_pk_bf16_f32 v164, v96, v97
	v_cvt_pk_bf16_f32 v165, v98, v99
	v_cvt_pk_bf16_f32 v166, v100, v101
	v_cvt_pk_bf16_f32 v167, v102, v103
	v_cvt_pk_bf16_f32 v168, v104, v105
	v_cvt_pk_bf16_f32 v169, v106, v107
	v_cvt_pk_bf16_f32 v170, v108, v109
	v_cvt_pk_bf16_f32 v171, v110, v111
	v_add_f32_e32 v193, v193, v0

.LBB0_1091:
	v_max3_f32 v14, v80, v81, v82
	v_max3_f32 v15, v96, v97, v98
	v_max3_f32 v14, v14, v83, v84
	v_max3_f32 v15, v15, v99, v100
	v_max3_f32 v14, v14, v85, v86
	v_max3_f32 v15, v15, v101, v102
	v_max3_f32 v14, v14, v87, v88
	v_max3_f32 v15, v15, v103, v104
	v_max3_f32 v14, v14, v89, v90
	v_max3_f32 v15, v15, v105, v106
	v_max3_f32 v14, v14, v91, v92
	v_max3_f32 v15, v15, v107, v108
	v_max_f32_e32 v140, v111, v111
	v_max_f32_e32 v141, v95, v95
	v_max3_f32 v14, v14, v93, v94
	v_max3_f32 v15, v15, v109, v110
	v_max_f32_e32 v140, v141, v140
	v_max3_f32 v14, v14, v15, v140
	v_cmp_lt_f32_e32 vcc, s33, v14
	s_cbranch_vccz .LBB0_1093
	ds_bpermute_b32 v15, v184, v14
	s_waitcnt lgkmcnt(0)
	v_max_f32_e32 v15, v15, v15
	v_max_f32_e32 v14, v14, v15
	v_max_f32_e32 v14, v14, v14
	v_max_f32_e32 v15, 0, v14
	v_exp_f32_e64 v14, -v15
	v_add_f32_e32 v195, v195, v15
	v_xor_b32_e32 v112, 0x80000000, v195
	v_sub_f32_e32 v95, v95, v15
	v_sub_f32_e32 v94, v94, v15
	v_sub_f32_e32 v93, v93, v15
	v_sub_f32_e32 v92, v92, v15
	v_sub_f32_e32 v91, v91, v15
	v_sub_f32_e32 v90, v90, v15
	v_sub_f32_e32 v89, v89, v15
	v_sub_f32_e32 v88, v88, v15
	v_sub_f32_e32 v87, v87, v15
	v_sub_f32_e32 v86, v86, v15
	v_sub_f32_e32 v85, v85, v15
	v_sub_f32_e32 v84, v84, v15
	v_sub_f32_e32 v83, v83, v15
	v_sub_f32_e32 v82, v82, v15
	v_sub_f32_e32 v81, v81, v15
	v_sub_f32_e32 v80, v80, v15
	v_pk_mul_f32 v[78:79], v[78:79], v[14:15] op_sel_hi:[1,0]
	v_pk_mul_f32 v[76:77], v[76:77], v[14:15] op_sel_hi:[1,0]
	v_pk_mul_f32 v[74:75], v[74:75], v[14:15] op_sel_hi:[1,0]
	v_pk_mul_f32 v[72:73], v[72:73], v[14:15] op_sel_hi:[1,0]
	v_pk_mul_f32 v[70:71], v[70:71], v[14:15] op_sel_hi:[1,0]
	v_pk_mul_f32 v[68:69], v[68:69], v[14:15] op_sel_hi:[1,0]
	v_pk_mul_f32 v[66:67], v[66:67], v[14:15] op_sel_hi:[1,0]
	v_pk_mul_f32 v[64:65], v[64:65], v[14:15] op_sel_hi:[1,0]
	v_pk_mul_f32 v[62:63], v[62:63], v[14:15] op_sel_hi:[1,0]
	v_pk_mul_f32 v[60:61], v[60:61], v[14:15] op_sel_hi:[1,0]
	v_pk_mul_f32 v[58:59], v[58:59], v[14:15] op_sel_hi:[1,0]
	v_pk_mul_f32 v[56:57], v[56:57], v[14:15] op_sel_hi:[1,0]
	v_pk_mul_f32 v[54:55], v[54:55], v[14:15] op_sel_hi:[1,0]
	v_pk_mul_f32 v[52:53], v[52:53], v[14:15] op_sel_hi:[1,0]
	v_pk_mul_f32 v[50:51], v[50:51], v[14:15] op_sel_hi:[1,0]
	v_pk_mul_f32 v[48:49], v[48:49], v[14:15] op_sel_hi:[1,0]
	v_pk_mul_f32 v[46:47], v[46:47], v[14:15] op_sel_hi:[1,0]
	v_pk_mul_f32 v[44:45], v[44:45], v[14:15] op_sel_hi:[1,0]
	v_pk_mul_f32 v[42:43], v[42:43], v[14:15] op_sel_hi:[1,0]
	v_pk_mul_f32 v[40:41], v[40:41], v[14:15] op_sel_hi:[1,0]
	v_pk_mul_f32 v[38:39], v[38:39], v[14:15] op_sel_hi:[1,0]
	v_pk_mul_f32 v[36:37], v[36:37], v[14:15] op_sel_hi:[1,0]
	v_pk_mul_f32 v[34:35], v[34:35], v[14:15] op_sel_hi:[1,0]
	v_pk_mul_f32 v[32:33], v[32:33], v[14:15] op_sel_hi:[1,0]
	v_pk_mul_f32 v[30:31], v[30:31], v[14:15] op_sel_hi:[1,0]
	v_pk_mul_f32 v[28:29], v[28:29], v[14:15] op_sel_hi:[1,0]
	v_pk_mul_f32 v[26:27], v[26:27], v[14:15] op_sel_hi:[1,0]
	v_pk_mul_f32 v[24:25], v[24:25], v[14:15] op_sel_hi:[1,0]
	v_pk_mul_f32 v[22:23], v[22:23], v[14:15] op_sel_hi:[1,0]
	v_pk_mul_f32 v[20:21], v[20:21], v[14:15] op_sel_hi:[1,0]
	v_pk_mul_f32 v[18:19], v[18:19], v[14:15] op_sel_hi:[1,0]
	v_pk_mul_f32 v[16:17], v[16:17], v[14:15] op_sel_hi:[1,0]
	v_sub_f32_e32 v111, v111, v15
	v_sub_f32_e32 v110, v110, v15
	v_sub_f32_e32 v109, v109, v15
	v_sub_f32_e32 v108, v108, v15
	v_sub_f32_e32 v107, v107, v15
	v_sub_f32_e32 v106, v106, v15
	v_sub_f32_e32 v105, v105, v15
	v_sub_f32_e32 v104, v104, v15
	v_sub_f32_e32 v103, v103, v15
	v_sub_f32_e32 v102, v102, v15
	v_sub_f32_e32 v101, v101, v15
	v_sub_f32_e32 v100, v100, v15
	v_sub_f32_e32 v99, v99, v15
	v_sub_f32_e32 v98, v98, v15
	v_sub_f32_e32 v97, v97, v15
	v_sub_f32_e32 v96, v96, v15
	v_mov_b32_e32 v113, v112
	v_mov_b32_e32 v114, v112
	v_mov_b32_e32 v115, v112
	v_mov_b32_e32 v116, v112
	v_mov_b32_e32 v117, v112
	v_mov_b32_e32 v118, v112
	v_mov_b32_e32 v119, v112
	v_mov_b32_e32 v120, v112
	v_mov_b32_e32 v121, v112
	v_mov_b32_e32 v122, v112
	v_mov_b32_e32 v123, v112
	v_mov_b32_e32 v124, v112
	v_mov_b32_e32 v125, v112
	v_mov_b32_e32 v126, v112
	v_mov_b32_e32 v127, v112
	v_mul_f32_e32 v193, v193, v14
.LBB0_1093:
	v_exp_f32_e32 v80, v80
	v_exp_f32_e32 v96, v96
	v_exp_f32_e32 v81, v81
	v_exp_f32_e32 v97, v97
	v_exp_f32_e32 v88, v88
	v_exp_f32_e32 v104, v104
	v_exp_f32_e32 v89, v89
	v_exp_f32_e32 v105, v105
	v_exp_f32_e32 v82, v82
	v_exp_f32_e32 v98, v98
	v_exp_f32_e32 v83, v83
	v_exp_f32_e32 v99, v99
	v_exp_f32_e32 v90, v90
	v_exp_f32_e32 v106, v106
	v_exp_f32_e32 v91, v91
	v_exp_f32_e32 v107, v107
	v_exp_f32_e32 v84, v84
	v_exp_f32_e32 v100, v100
	v_exp_f32_e32 v85, v85
	v_exp_f32_e32 v101, v101
	v_exp_f32_e32 v92, v92
	v_exp_f32_e32 v108, v108
	v_exp_f32_e32 v93, v93
	v_exp_f32_e32 v109, v109
	v_exp_f32_e32 v86, v86
	v_exp_f32_e32 v102, v102
	v_exp_f32_e32 v87, v87
	v_exp_f32_e32 v103, v103
	v_exp_f32_e32 v94, v94
	v_exp_f32_e32 v110, v110
	v_exp_f32_e32 v95, v95
	v_exp_f32_e32 v111, v111
	v_pk_add_f32 v[140:141], v[80:81], v[96:97]
	v_pk_add_f32 v[142:143], v[82:83], v[98:99]
	v_pk_add_f32 v[144:145], v[84:85], v[100:101]
	v_pk_add_f32 v[146:147], v[86:87], v[102:103]
	v_pk_add_f32 v[148:149], v[88:89], v[104:105]
	v_pk_add_f32 v[150:151], v[90:91], v[106:107]
	v_pk_add_f32 v[152:153], v[92:93], v[108:109]
	v_pk_add_f32 v[154:155], v[94:95], v[110:111]
	v_pk_add_f32 v[140:141], v[140:141], v[142:143]
	v_pk_add_f32 v[144:145], v[144:145], v[146:147]
	v_pk_add_f32 v[148:149], v[148:149], v[150:151]
	v_pk_add_f32 v[152:153], v[152:153], v[154:155]
	v_pk_add_f32 v[140:141], v[140:141], v[144:145]
	v_pk_add_f32 v[148:149], v[148:149], v[152:153]
	v_pk_add_f32 v[140:141], v[140:141], v[148:149]
	v_add_f32_e32 v14, v140, v141
	v_cvt_pk_bf16_f32 v140, v80, v81
	v_cvt_pk_bf16_f32 v141, v82, v83
	v_cvt_pk_bf16_f32 v142, v84, v85
	v_cvt_pk_bf16_f32 v143, v86, v87
	v_cvt_pk_bf16_f32 v144, v88, v89
	v_cvt_pk_bf16_f32 v145, v90, v91
	v_cvt_pk_bf16_f32 v146, v92, v93
	v_cvt_pk_bf16_f32 v147, v94, v95
	v_cvt_pk_bf16_f32 v148, v96, v97
	v_cvt_pk_bf16_f32 v149, v98, v99
	v_cvt_pk_bf16_f32 v150, v100, v101
	v_cvt_pk_bf16_f32 v151, v102, v103
	v_cvt_pk_bf16_f32 v152, v104, v105
	v_cvt_pk_bf16_f32 v153, v106, v107
	v_cvt_pk_bf16_f32 v154, v108, v109
	v_cvt_pk_bf16_f32 v155, v110, v111
	v_add_f32_e32 v193, v193, v14
